# DSA item order batch-element major (512 rounds of one batch element back to back) for L2 locality
# baseline (speedup 1.0000x reference)
; #define LAS __attribute__((address_space(3)))
; __device__ __forceinline__ float bf2f(u16 b) { return __uint_as_float(((unsigned)b) << 16); }
;     ...
;     const int t0 = rq * 8, nmax = t0 + 8, ntile32 = (nmax + 31) >> 5;
;     const u16* prow = p.proj + (size_t)bl * SEQ * NP;
;     LAS float* sc = (LAS float*)lds;
;     { const int c32 = lane & 31, hi = lane >> 5;
;       bf16x8 qa[4];
;       { const u16* qp = prow + (size_t)(t0 + (c32 >> 2)) * NP + C_QI + (c32 & 3) * 64 + 8 * hi;
; #pragma unroll
;         for (int ks = 0; ks < 4; ++ks) qa[ks] = *(const bf16x8*)(qp + ks * 16); }
;       float wv[16];
; #pragma unroll
;       for (int r = 0; r < 16; ++r) wv[r] = 0.5f * bf2f(prow[(size_t)(t0 + 2 * (r >> 2) + hi) * NP + C_WI + (r & 3)]);
; #pragma unroll
;       for (int r = 0; r < 16; ++r) wv[r] *= 0.125f;
;       auto ldb = [&](bf16x8 (&kk)[4][4], int i0) {
; #pragma unroll
;           for (int j = 0; j < 4; ++j) { int T = wid + 8 * (i0 + j); T = T < ntile32 ? T : ntile32 - 1; const u16* kp = p.kiP + (((size_t)bl * 128 + T) * 256 + lane) * 8;
; #pragma unroll
;               for (int ks = 0; ks < 4; ++ks) kk[j][ks] = *(const bf16x8*)(kp + ks * 512); } };
;     ...
;         else if (it < N_D + N_B) { if (!(tmask & 2)) continue; const int j = it - N_D; const int rq = 511 - (j >> 2), bl = j & 3; item_dsa(p, bl, rq, lds, smask); }
.LBB0_178:
	s_and_b64 vcc, exec, s[38:39]
	s_cbranch_vccz .LBB0_970
	s_sub_i32 s0, s58, 0x100
	s_lshr_b32 s37, s0, 9
	s_and_b32 s0, s0, 0x1ff
	s_lshl_b32 s0, s0, 3
	s_addk_i32 s0, 0x200
	v_mov_b32_e32 v174, v198
	s_sub_i32 s30, 0x11f8, s0
	s_sub_i32 s0, 0x1218, s0
	s_mul_i32 s1, s37, 0x5800000
	s_add_u32 s54, s14, s1
	v_readfirstlane_b32 s59, v174
	s_addc_u32 s55, s15, 0
	s_ashr_i32 s64, s59, 6
	s_lshr_b32 s0, s0, 5
	s_sub_i32 s1, s0, s64
	s_add_i32 s1, s1, 7
	s_ashr_i32 s1, s1, 3
	s_cmp_lt_i32 s1, 1
	v_and_b32_e32 v163, 63, v174
	s_cbranch_scc1 .LBB0_198
	v_lshrrev_b32_e32 v14, 5, v163
	v_or_b32_e32 v0, s30, v14
	v_mul_i32_i24_e32 v0, 0x5800, v0
	v_lshl_add_u64 v[2:3], s[54:55], 0, v[0:1]
	v_add_co_u32_e32 v4, vcc, 0x1000, v2
	s_mov_b32 s20, 0xc000
	s_nop 0
	v_addc_co_u32_e32 v5, vcc, 0, v3, vcc
	v_bfe_u32 v0, v174, 2, 3
	v_add_co_u32_e32 v6, vcc, s20, v2
	v_or_b32_e32 v0, s30, v0
	s_nop 0
	v_addc_co_u32_e32 v7, vcc, 0, v3, vcc
	s_mov_b32 s20, 0x17000
	v_mul_i32_i24_e32 v0, 0x2c00, v0
	v_add_co_u32_e32 v8, vcc, s20, v2
	v_lshl_add_u64 v[10:11], v[0:1], 1, s[54:55]
	v_lshlrev_b32_e32 v0, 7, v163
	v_addc_co_u32_e32 v9, vcc, 0, v3, vcc
	s_mov_b32 s20, 0x22000
	v_and_b32_e32 v0, 0x180, v0
	v_add_co_u32_e32 v2, vcc, s20, v2
	v_lshl_add_u64 v[10:11], v[10:11], 0, v[0:1]
	v_lshlrev_b32_e32 v0, 4, v14
	v_addc_co_u32_e32 v3, vcc, 0, v3, vcc
	v_lshl_add_u64 v[10:11], v[10:11], 0, v[0:1]
	s_mov_b64 s[22:23], 0x1100
	s_movk_i32 s21, 0x1000
	s_add_i32 s20, s0, -1
	v_lshl_add_u64 v[12:13], v[10:11], 0, s[22:23]
	v_add_co_u32_e32 v10, vcc, s21, v10
	s_add_i32 s21, s64, 24
	s_min_i32 s22, s21, s20
	s_ashr_i32 s23, s22, 31
	s_lshl_b32 s24, s37, 15
	s_lshl_b64 s[22:23], s[22:23], 8
	s_add_u32 s21, s22, s24
	global_load_dwordx2 v[4:5], v[4:5], off offset:896
	s_nop 0
	global_load_dwordx2 v[6:7], v[6:7], off offset:896
	s_nop 0
	global_load_dwordx2 v[8:9], v[8:9], off offset:896
	s_nop 0
	global_load_dwordx2 v[2:3], v[2:3], off offset:896
	s_nop 0
	global_load_dwordx4 v[18:21], v[12:13], off offset:64
	global_load_dwordx4 v[22:25], v[12:13], off offset:32
	v_addc_co_u32_e32 v11, vcc, 0, v11, vcc
	global_load_dwordx4 v[26:29], v[12:13], off offset:96
	global_load_dwordx4 v[30:33], v[10:11], off offset:256
	s_addc_u32 s22, s23, 0
	v_or_b32_e32 v10, s21, v163
	s_add_i32 s21, s64, 16
	v_mov_b32_e32 v11, s22
	s_min_i32 s22, s21, s20
	v_readlane_b32 s40, v251, 1
	s_ashr_i32 s23, s22, 31
	v_readlane_b32 s41, v251, 2
	s_lshl_b64 s[22:23], s[22:23], 8
	s_add_u32 s21, s22, s24
	v_lshl_add_u64 v[10:11], v[10:11], 4, s[40:41]
	global_load_dwordx4 v[34:37], v[10:11], off offset:3072
	global_load_dwordx4 v[38:41], v[10:11], off offset:2048
	global_load_dwordx4 v[42:45], v[10:11], off offset:1024
	global_load_dwordx4 v[46:49], v[10:11], off
	s_addc_u32 s22, s23, 0
	v_or_b32_e32 v10, s21, v163
	s_add_i32 s21, s64, 8
	v_mov_b32_e32 v11, s22
	s_min_i32 s22, s21, s20
	s_ashr_i32 s23, s22, 31
	s_lshl_b64 s[22:23], s[22:23], 8
	s_add_u32 s21, s22, s24
	v_lshl_add_u64 v[10:11], v[10:11], 4, s[40:41]
	s_addc_u32 s22, s23, 0
	global_load_dwordx4 v[50:53], v[10:11], off offset:3072
	global_load_dwordx4 v[54:57], v[10:11], off offset:2048
	global_load_dwordx4 v[58:61], v[10:11], off offset:1024
	global_load_dwordx4 v[62:65], v[10:11], off
	v_mov_b32_e32 v11, s22
	s_min_i32 s22, s64, s20
	s_ashr_i32 s23, s22, 31
	s_lshl_b64 s[22:23], s[22:23], 8
	v_or_b32_e32 v10, s21, v163
	s_add_u32 s21, s22, s24
	v_lshl_add_u64 v[10:11], v[10:11], 4, s[40:41]
	s_addc_u32 s22, s23, 0
	global_load_dwordx4 v[82:85], v[10:11], off offset:3072
	global_load_dwordx4 v[86:89], v[10:11], off offset:2048
	global_load_dwordx4 v[90:93], v[10:11], off offset:1024
	global_load_dwordx4 v[94:97], v[10:11], off
	v_or_b32_e32 v10, s21, v163
	v_mov_b32_e32 v11, s22
	v_lshl_add_u64 v[10:11], v[10:11], 4, s[40:41]
	global_load_dwordx4 v[114:117], v[10:11], off offset:3072
	global_load_dwordx4 v[118:121], v[10:11], off offset:2048
	global_load_dwordx4 v[122:125], v[10:11], off offset:1024
	global_load_dwordx4 v[126:129], v[10:11], off
	s_lshl_b32 s23, s64, 7
	s_mov_b32 s21, 0
	s_add_i32 s22, s64, 0x58
	v_readlane_b32 s42, v251, 3
	v_readlane_b32 s43, v251, 4
	v_readlane_b32 s44, v251, 5
	v_readlane_b32 s45, v251, 6
	v_readlane_b32 s46, v251, 7
	v_readlane_b32 s47, v251, 8
	s_waitcnt vmcnt(0)
	v_lshlrev_b32_e32 v0, 16, v4
	v_mul_f32_e32 v0, 0.5, v0
	v_mul_f32_e32 v175, 0x3e000000, v0
	s_waitcnt vmcnt(20)
	v_lshlrev_b32_e32 v16, 16, v2
	v_and_b32_e32 v2, 0xffff0000, v2
	v_or_b32_e32 v0, s24, v163
	v_mul_f32_e32 v2, 0.5, v2
	v_lshlrev_b32_e32 v0, 4, v0
	v_and_b32_e32 v4, 0xffff0000, v4
	v_lshlrev_b32_e32 v10, 16, v5
	v_and_b32_e32 v5, 0xffff0000, v5
	v_lshlrev_b32_e32 v11, 16, v6
	v_and_b32_e32 v6, 0xffff0000, v6
	v_lshlrev_b32_e32 v12, 16, v7
	v_and_b32_e32 v7, 0xffff0000, v7
	v_lshlrev_b32_e32 v13, 16, v8
	v_and_b32_e32 v8, 0xffff0000, v8
	v_lshlrev_b32_e32 v15, 16, v9
	v_and_b32_e32 v9, 0xffff0000, v9
	v_lshlrev_b32_e32 v17, 16, v3
	v_and_b32_e32 v3, 0xffff0000, v3
	v_mul_f32_e32 v189, 0x3e000000, v2
	v_and_b32_e32 v2, 31, v174
	v_lshl_add_u64 v[172:173], s[40:41], 0, v[0:1]
	v_lshl_add_u32 v0, v14, 14, s23
	v_mul_f32_e32 v4, 0.5, v4
	v_mul_f32_e32 v10, 0.5, v10
	v_mul_f32_e32 v5, 0.5, v5
	v_mul_f32_e32 v11, 0.5, v11
	v_mul_f32_e32 v6, 0.5, v6
	v_mul_f32_e32 v12, 0.5, v12
	v_mul_f32_e32 v7, 0.5, v7
	v_mul_f32_e32 v13, 0.5, v13
	v_mul_f32_e32 v8, 0.5, v8
	v_mul_f32_e32 v15, 0.5, v15
	v_mul_f32_e32 v9, 0.5, v9
	v_mul_f32_e32 v16, 0.5, v16
	v_mul_f32_e32 v17, 0.5, v17
	v_mul_f32_e32 v3, 0.5, v3
	v_lshl_or_b32 v0, v2, 2, v0
	v_mul_f32_e32 v176, 0x3e000000, v4
	v_mul_f32_e32 v177, 0x3e000000, v10
	v_mul_f32_e32 v178, 0x3e000000, v5
	v_mul_f32_e32 v179, 0x3e000000, v11
	v_mul_f32_e32 v181, 0x3e000000, v6
	v_mul_f32_e32 v182, 0x3e000000, v12
	v_mul_f32_e32 v183, 0x3e000000, v7
	v_mul_f32_e32 v184, 0x3e000000, v13
	v_mul_f32_e32 v185, 0x3e000000, v8
	v_mul_f32_e32 v186, 0x3e000000, v15
	v_mul_f32_e32 v187, 0x3e000000, v9
	v_mul_f32_e32 v188, 0x3e000000, v16
	v_mul_f32_e32 v190, 0x3e000000, v17
	v_mul_f32_e32 v191, 0x3e000000, v3
	v_add_u32_e32 v0, 0, v0
	s_branch .LBB0_182
